# out-proj drain epilogue under de-synchronised halves: second block's residual loads prefetched while the first block is processed (register double buffer)
# baseline (speedup 1.0000x reference)
.LBB0_411:
	s_mov_b32 s99, s10
	s_lshl_b32 s28, s10, 17
	v_lshl_add_u64 v[98:99], v[96:97], 0, s[28:29]
	s_lshl_b32 s28, s10, 6
	s_add_i32 s28, s28, s31
	v_cndmask_b32_e64 v64, 0, 1, s[22:23]
	s_mul_i32 s12, s28, 0x410
	s_and_b64 vcc, exec, s[80:81]
	v_cmp_ne_u32_e64 s[6:7], 1, v64
	s_mov_b64 s[8:9], -1
	s_cbranch_vccz .LBB0_461
	v_lshlrev_b64 v[64:65], 1, v[98:99]
	v_lshl_add_u64 v[68:69], s[20:21], 0, v[64:65]
	global_load_dwordx2 v[102:103], v[68:69], off
	v_lshl_add_u64 v[64:65], s[34:35], 0, v[64:65]
	v_mov_b32_e32 v100, 0
	s_and_b64 vcc, exec, s[6:7]
	v_mov_b32_e32 v104, 0
	v_mov_b32_e32 v105, 0
	s_cbranch_vccnz .LBB0_414
	global_load_dwordx2 v[104:105], v[64:65], off

.LBB0_461:
	v_cndmask_b32_e64 v64, 0, 1, s[42:43]
	s_and_b64 vcc, exec, s[8:9]
	v_cmp_ne_u32_e64 s[8:9], 1, v64
	s_cbranch_vccz .LBB0_410
	s_cmp_lg_u32 s99, 0
	s_cbranch_scc1 .Ldrpf_a_second
	v_lshl_add_u64 v[64:65], v[98:99], 2, s[68:69]
	v_add_co_u32_e32 v66, vcc, 0x10000, v64
	v_add_u32_e32 v100, s12, v110
	s_nop 0
	v_addc_co_u32_e32 v67, vcc, 0, v65, vcc
	global_load_dwordx4 v[92:95], v[64:65], off
	global_load_dwordx4 v[88:91], v[66:67], off
	v_add_co_u32_e32 v66, vcc, 0x20000, v64
	s_nop 1
	v_addc_co_u32_e32 v67, vcc, 0, v65, vcc
	v_add_co_u32_e32 v68, vcc, 0x30000, v64
	s_nop 1
	v_addc_co_u32_e32 v69, vcc, 0, v65, vcc
	global_load_dwordx4 v[84:87], v[66:67], off
	global_load_dwordx4 v[80:83], v[68:69], off
	v_add_co_u32_e32 v66, vcc, 0x40000, v64
	s_nop 1
	v_addc_co_u32_e32 v67, vcc, 0, v65, vcc
	v_add_co_u32_e32 v68, vcc, 0x50000, v64
	s_nop 1
	v_addc_co_u32_e32 v69, vcc, 0, v65, vcc
	global_load_dwordx4 v[76:79], v[66:67], off
	global_load_dwordx4 v[72:75], v[68:69], off
	v_add_co_u32_e32 v66, vcc, 0x60000, v64
	s_nop 1
	v_addc_co_u32_e32 v67, vcc, 0, v65, vcc
	v_add_co_u32_e32 v64, vcc, 0x70000, v64
	s_nop 1
	v_addc_co_u32_e32 v65, vcc, 0, v65, vcc
	global_load_dwordx4 v[68:71], v[66:67], off
	s_nop 0
	global_load_dwordx4 v[64:67], v[64:65], off
	s_mov_b64 s[100:101], 0x20000
	v_lshl_add_u64 v[170:171], v[98:99], 0, s[100:101]
	v_lshl_add_u64 v[170:171], v[170:171], 2, s[68:69]
	global_load_dwordx4 v[166:169], v[170:171], off
	s_mov_b64 s[100:101], 0x10000
	v_lshl_add_u64 v[172:173], v[170:171], 0, s[100:101]
	global_load_dwordx4 v[162:165], v[172:173], off
	s_mov_b64 s[100:101], 0x20000
	v_lshl_add_u64 v[172:173], v[170:171], 0, s[100:101]
	global_load_dwordx4 v[158:161], v[172:173], off
	s_mov_b64 s[100:101], 0x30000
	v_lshl_add_u64 v[172:173], v[170:171], 0, s[100:101]
	global_load_dwordx4 v[154:157], v[172:173], off
	s_mov_b64 s[100:101], 0x40000
	v_lshl_add_u64 v[172:173], v[170:171], 0, s[100:101]
	global_load_dwordx4 v[150:153], v[172:173], off
	s_mov_b64 s[100:101], 0x50000
	v_lshl_add_u64 v[172:173], v[170:171], 0, s[100:101]
	global_load_dwordx4 v[146:149], v[172:173], off
	s_mov_b64 s[100:101], 0x60000
	v_lshl_add_u64 v[172:173], v[170:171], 0, s[100:101]
	global_load_dwordx4 v[142:145], v[172:173], off
	s_mov_b64 s[100:101], 0x70000
	v_lshl_add_u64 v[172:173], v[170:171], 0, s[100:101]
	global_load_dwordx4 v[138:141], v[172:173], off
	s_branch .Ldrpf_a_join
.Ldrpf_a_second:
	v_add_u32_e32 v100, s12, v110
	s_waitcnt vmcnt(0)
	v_mov_b32_e32 v64, v138
	v_mov_b32_e32 v65, v139
	v_mov_b32_e32 v66, v140
	v_mov_b32_e32 v67, v141
	v_mov_b32_e32 v68, v142
	v_mov_b32_e32 v69, v143
	v_mov_b32_e32 v70, v144
	v_mov_b32_e32 v71, v145
	v_mov_b32_e32 v72, v146
	v_mov_b32_e32 v73, v147
	v_mov_b32_e32 v74, v148
	v_mov_b32_e32 v75, v149
	v_mov_b32_e32 v76, v150
	v_mov_b32_e32 v77, v151
	v_mov_b32_e32 v78, v152
	v_mov_b32_e32 v79, v153
	v_mov_b32_e32 v80, v154
	v_mov_b32_e32 v81, v155
	v_mov_b32_e32 v82, v156
	v_mov_b32_e32 v83, v157
	v_mov_b32_e32 v84, v158
	v_mov_b32_e32 v85, v159
	v_mov_b32_e32 v86, v160
	v_mov_b32_e32 v87, v161
	v_mov_b32_e32 v88, v162
	v_mov_b32_e32 v89, v163
	v_mov_b32_e32 v90, v164
	v_mov_b32_e32 v91, v165
	v_mov_b32_e32 v92, v166
	v_mov_b32_e32 v93, v167
	v_mov_b32_e32 v94, v168
	v_mov_b32_e32 v95, v169
.Ldrpf_a_join:
	ds_read_b128 v[102:105], v100
	s_cmp_lg_u32 s99, 0
	s_cbranch_scc1 .Ldrw_a0_n
	s_waitcnt vmcnt(15)
	s_branch .Ldrw_a0_e

.LBB0_470:
	ds_read_b128 v[92:95], v100 offset:8320
	s_mov_b64 s[46:47], 0x4000
	s_cmp_lg_u32 s99, 0
	s_cbranch_scc1 .Ldrw_a1_n
	s_waitcnt vmcnt(14)
	s_branch .Ldrw_a1_e

.LBB0_478:
	ds_read_b128 v[88:91], v100 offset:16640
	s_mov_b64 s[46:47], 0x8000
	s_cmp_lg_u32 s99, 0
	s_cbranch_scc1 .Ldrw_a2_n
	s_waitcnt vmcnt(13)
	s_branch .Ldrw_a2_e

.LBB0_486:
	ds_read_b128 v[84:87], v100 offset:24960
	s_mov_b64 s[46:47], 0xc000
	s_cmp_lg_u32 s99, 0
	s_cbranch_scc1 .Ldrw_a3_n
	s_waitcnt vmcnt(12)
	s_branch .Ldrw_a3_e

.LBB0_494:
	ds_read_b128 v[80:83], v100 offset:33280
	s_mov_b64 s[46:47], 0x10000
	s_cmp_lg_u32 s99, 0
	s_cbranch_scc1 .Ldrw_a4_n
	s_waitcnt vmcnt(11)
	s_branch .Ldrw_a4_e

.LBB0_502:
	ds_read_b128 v[76:79], v100 offset:41600
	s_mov_b64 s[46:47], 0x14000
	s_cmp_lg_u32 s99, 0
	s_cbranch_scc1 .Ldrw_a5_n
	s_waitcnt vmcnt(10)
	s_branch .Ldrw_a5_e

.LBB0_510:
	ds_read_b128 v[72:75], v100 offset:49920
	s_mov_b64 s[46:47], 0x18000
	s_cmp_lg_u32 s99, 0
	s_cbranch_scc1 .Ldrw_a6_n
	s_waitcnt vmcnt(9)
	s_branch .Ldrw_a6_e

.LBB0_518:
	ds_read_b128 v[68:71], v100 offset:58240
	s_mov_b64 s[46:47], 0x1c000
	s_cmp_lg_u32 s99, 0
	s_cbranch_scc1 .Ldrw_a7_n
	s_waitcnt vmcnt(8)
	s_branch .Ldrw_a7_e

.LBB0_528:
	s_mov_b32 s99, s10
	s_lshl_b32 s28, s10, 17
	v_lshl_add_u64 v[34:35], v[32:33], 0, s[28:29]
	s_lshl_b32 s28, s10, 6
	s_add_i32 s42, s28, s31
	s_mulk_i32 s42, 0x410
	s_and_b64 vcc, exec, s[80:81]
	s_mov_b64 s[10:11], -1
	s_cbranch_vccz .LBB0_578
	v_lshlrev_b64 v[0:1], 1, v[34:35]
	v_lshl_add_u64 v[4:5], s[20:21], 0, v[0:1]
	global_load_dwordx2 v[38:39], v[4:5], off
	v_lshl_add_u64 v[0:1], s[34:35], 0, v[0:1]
	v_mov_b32_e32 v36, 0
	s_and_b64 vcc, exec, s[6:7]
	v_mov_b32_e32 v40, 0
	v_mov_b32_e32 v41, 0
	s_cbranch_vccnz .LBB0_531
	global_load_dwordx2 v[40:41], v[0:1], off

.LBB0_578:
	s_and_b64 vcc, exec, s[10:11]
	s_cbranch_vccz .LBB0_527
	s_cmp_lg_u32 s99, 0
	s_cbranch_scc1 .Ldrpf_b_second
	v_lshl_add_u64 v[0:1], v[34:35], 2, s[68:69]
	v_add_co_u32_e32 v2, vcc, 0x10000, v0
	v_add_u32_e32 v36, s42, v110
	s_nop 0
	v_addc_co_u32_e32 v3, vcc, 0, v1, vcc
	global_load_dwordx4 v[28:31], v[0:1], off
	global_load_dwordx4 v[24:27], v[2:3], off
	v_add_co_u32_e32 v2, vcc, 0x20000, v0
	s_nop 1
	v_addc_co_u32_e32 v3, vcc, 0, v1, vcc
	v_add_co_u32_e32 v4, vcc, 0x30000, v0
	s_nop 1
	v_addc_co_u32_e32 v5, vcc, 0, v1, vcc
	global_load_dwordx4 v[20:23], v[2:3], off
	global_load_dwordx4 v[16:19], v[4:5], off
	v_add_co_u32_e32 v2, vcc, 0x40000, v0
	s_nop 1
	v_addc_co_u32_e32 v3, vcc, 0, v1, vcc
	v_add_co_u32_e32 v4, vcc, 0x50000, v0
	s_nop 1
	v_addc_co_u32_e32 v5, vcc, 0, v1, vcc
	global_load_dwordx4 v[12:15], v[2:3], off
	global_load_dwordx4 v[8:11], v[4:5], off
	v_add_co_u32_e32 v2, vcc, 0x60000, v0
	s_nop 1
	v_addc_co_u32_e32 v3, vcc, 0, v1, vcc
	v_add_co_u32_e32 v0, vcc, 0x70000, v0
	s_nop 1
	v_addc_co_u32_e32 v1, vcc, 0, v1, vcc
	global_load_dwordx4 v[4:7], v[2:3], off
	s_nop 0
	global_load_dwordx4 v[0:3], v[0:1], off
	s_mov_b64 s[100:101], 0x20000
	v_lshl_add_u64 v[170:171], v[34:35], 0, s[100:101]
	v_lshl_add_u64 v[170:171], v[170:171], 2, s[68:69]
	global_load_dwordx4 v[166:169], v[170:171], off
	s_mov_b64 s[100:101], 0x10000
	v_lshl_add_u64 v[172:173], v[170:171], 0, s[100:101]
	global_load_dwordx4 v[162:165], v[172:173], off
	s_mov_b64 s[100:101], 0x20000
	v_lshl_add_u64 v[172:173], v[170:171], 0, s[100:101]
	global_load_dwordx4 v[158:161], v[172:173], off
	s_mov_b64 s[100:101], 0x30000
	v_lshl_add_u64 v[172:173], v[170:171], 0, s[100:101]
	global_load_dwordx4 v[154:157], v[172:173], off
	s_mov_b64 s[100:101], 0x40000
	v_lshl_add_u64 v[172:173], v[170:171], 0, s[100:101]
	global_load_dwordx4 v[150:153], v[172:173], off
	s_mov_b64 s[100:101], 0x50000
	v_lshl_add_u64 v[172:173], v[170:171], 0, s[100:101]
	global_load_dwordx4 v[146:149], v[172:173], off
	s_mov_b64 s[100:101], 0x60000
	v_lshl_add_u64 v[172:173], v[170:171], 0, s[100:101]
	global_load_dwordx4 v[142:145], v[172:173], off
	s_mov_b64 s[100:101], 0x70000
	v_lshl_add_u64 v[172:173], v[170:171], 0, s[100:101]
	global_load_dwordx4 v[138:141], v[172:173], off
	s_branch .Ldrpf_b_join
.Ldrpf_b_second:
	v_add_u32_e32 v36, s42, v110
	s_waitcnt vmcnt(0)
	v_mov_b32_e32 v0, v138
	v_mov_b32_e32 v1, v139
	v_mov_b32_e32 v2, v140
	v_mov_b32_e32 v3, v141
	v_mov_b32_e32 v4, v142
	v_mov_b32_e32 v5, v143
	v_mov_b32_e32 v6, v144
	v_mov_b32_e32 v7, v145
	v_mov_b32_e32 v8, v146
	v_mov_b32_e32 v9, v147
	v_mov_b32_e32 v10, v148
	v_mov_b32_e32 v11, v149
	v_mov_b32_e32 v12, v150
	v_mov_b32_e32 v13, v151
	v_mov_b32_e32 v14, v152
	v_mov_b32_e32 v15, v153
	v_mov_b32_e32 v16, v154
	v_mov_b32_e32 v17, v155
	v_mov_b32_e32 v18, v156
	v_mov_b32_e32 v19, v157
	v_mov_b32_e32 v20, v158
	v_mov_b32_e32 v21, v159
	v_mov_b32_e32 v22, v160
	v_mov_b32_e32 v23, v161
	v_mov_b32_e32 v24, v162
	v_mov_b32_e32 v25, v163
	v_mov_b32_e32 v26, v164
	v_mov_b32_e32 v27, v165
	v_mov_b32_e32 v28, v166
	v_mov_b32_e32 v29, v167
	v_mov_b32_e32 v30, v168
	v_mov_b32_e32 v31, v169
.Ldrpf_b_join:
	ds_read_b128 v[38:41], v36
	s_cmp_lg_u32 s99, 0
	s_cbranch_scc1 .Ldrw_b0_n
	s_waitcnt vmcnt(15)
	s_branch .Ldrw_b0_e

.LBB0_587:
	ds_read_b128 v[28:31], v36 offset:8320
	s_mov_b64 s[42:43], 0x4000
	s_cmp_lg_u32 s99, 0
	s_cbranch_scc1 .Ldrw_b1_n
	s_waitcnt vmcnt(14)
	s_branch .Ldrw_b1_e

.LBB0_595:
	ds_read_b128 v[24:27], v36 offset:16640
	s_mov_b64 s[42:43], 0x8000
	s_cmp_lg_u32 s99, 0
	s_cbranch_scc1 .Ldrw_b2_n
	s_waitcnt vmcnt(13)
	s_branch .Ldrw_b2_e

.LBB0_603:
	ds_read_b128 v[20:23], v36 offset:24960
	s_mov_b64 s[42:43], 0xc000
	s_cmp_lg_u32 s99, 0
	s_cbranch_scc1 .Ldrw_b3_n
	s_waitcnt vmcnt(12)
	s_branch .Ldrw_b3_e

.LBB0_611:
	ds_read_b128 v[16:19], v36 offset:33280
	s_mov_b64 s[42:43], 0x10000
	s_cmp_lg_u32 s99, 0
	s_cbranch_scc1 .Ldrw_b4_n
	s_waitcnt vmcnt(11)
	s_branch .Ldrw_b4_e

.LBB0_619:
	ds_read_b128 v[12:15], v36 offset:41600
	s_mov_b64 s[42:43], 0x14000
	s_cmp_lg_u32 s99, 0
	s_cbranch_scc1 .Ldrw_b5_n
	s_waitcnt vmcnt(10)
	s_branch .Ldrw_b5_e

.LBB0_627:
	ds_read_b128 v[8:11], v36 offset:49920
	s_mov_b64 s[42:43], 0x18000
	s_cmp_lg_u32 s99, 0
	s_cbranch_scc1 .Ldrw_b6_n
	s_waitcnt vmcnt(9)
	s_branch .Ldrw_b6_e

.LBB0_635:
	ds_read_b128 v[4:7], v36 offset:58240
	s_mov_b64 s[42:43], 0x1c000
	s_cmp_lg_u32 s99, 0
	s_cbranch_scc1 .Ldrw_b7_n
	s_waitcnt vmcnt(8)
	s_branch .Ldrw_b7_e
